# SSD item prologue de-serialised: counted wait for the first scalar load, full drain moved to the prologue end so the scan-wave dt loads overlap the row loads
# baseline (speedup 1.0000x reference)
; #define SSD_ISSUE_DT(c_) do { const int c__ = (c_); const float* dp = dtraw + (rowbase + (size_t)c__ * 128 + lane) * 32 + head; dtn0 = dp[0]; dtn1 = dp[64 * 32]; } while (0)
; __device__ __forceinline__ void ssd_item(const Params& p, LAS unsigned char* lds, int bl, int head, int dry) {
;     ...
;     const float Ah = -__expf(p.a_log[head]), Dh = p.d_skip[head], dtb = p.dt_bias[head];
;     const int g = head >> 2; const size_t rowbase = (size_t)bl * SEQ;
;     const int pt = w >> 2, nt = w & 3;
;     const int rsub = 4 * (lane >> 5), cl = lane & 31;
;     const bool cact = tid < 320; const int cq = tid % 80, rg = (tid / 80) & 3, rgc = tid < 320 ? tid / 80 : 3;
;     int kind, n4, col, ch;
;     if (cq < 16) { kind = 0; n4 = 4 * cq; col = COL_XBC + head * 64 + n4; ch = head * 64 + n4; }
;     else if (cq < 48) { kind = 1; n4 = 4 * (cq - 16); col = COL_XBC + 2048 + g * 128 + n4; ch = 2048 + g * 128 + n4; }
;     else { kind = 2; n4 = 4 * (cq - 48); col = COL_XBC + 3072 + g * 128 + n4; ch = 3072 + g * 128 + n4; }
;     f32x4 cw0, cw1, cw2, cw3, cbv;
;     cw0 = *(const f32x4*)(p.ssd_conv_w + ch); cw1 = *(const f32x4*)(p.ssd_conv_w + CONV_DIM + ch); cw2 = *(const f32x4*)(p.ssd_conv_w + 2 * CONV_DIM + ch); cw3 = *(const f32x4*)(p.ssd_conv_w + 3 * CONV_DIM + ch);
;     cbv = *(const f32x4*)(p.ssd_conv_b + ch);
;     u32x2 raw[35]; float dtn0 = 0.f, dtn1 = 0.f; u32x2 zr[4];
;     const size_t pstep = cact ? (size_t)PLD : (size_t)0;
;     const int ti_d = w >> 1, pc_d = w & 1;
;     ...
;     SSD_ISSUE_DT(0); SSD_ISSUE_RAW(0);
.LBB0_210:
	s_andn2_saveexec_b64 s[0:1], s[0:1]
	v_lshl_add_u32 v0, s12, 6, v2
	v_add_u32_e32 v6, 0x800, v0
	v_mov_b32_e32 v4, 0
	s_andn2_b64 s[4:5], s[4:5], exec
	s_or_b64 exec, exec, s[0:1]
	v_ashrrev_i32_e32 v1, 31, v0
	v_readlane_b32 s6, v245, 25
	v_readlane_b32 s0, v243, 42
	v_lshlrev_b64 v[0:1], 2, v[0:1]
	v_readlane_b32 s56, v245, 29
	v_readlane_b32 s7, v245, 26
	s_ashr_i32 s0, s0, 5
	v_readlane_b32 s62, v245, 35
	v_readlane_b32 s63, v245, 36
	v_lshl_add_u64 v[10:11], s[6:7], 0, v[0:1]
	v_readlane_b32 s6, v245, 27
	s_ashr_i32 s1, s0, 31
	v_lshl_add_u64 v[8:9], s[62:63], 0, v[0:1]
	v_readlane_b32 s7, v245, 28
	s_lshl_b64 s[54:55], s[0:1], 12
	global_load_dwordx4 v[48:51], v[8:9], off
	global_load_dwordx4 v[52:55], v[10:11], off
	v_lshl_add_u64 v[8:9], s[6:7], 0, v[0:1]
	v_readlane_b32 s6, v245, 45
	s_movk_i32 s1, 0x140
	v_readlane_b32 s7, v245, 46
	v_cmp_gt_i32_e64 s[40:41], s1, v246
	s_mul_hi_i32 s1, s0, 0x6400000
	s_mul_i32 s0, s0, 0x6400000
	v_readlane_b32 s64, v245, 37
	v_readlane_b32 s65, v245, 38
	v_lshl_add_u64 v[10:11], s[6:7], 0, v[0:1]
	v_lshl_add_u32 v163, v3, 5, -3
	v_add_u32_e32 v163, s99, v163
	s_add_u32 s0, s14, s0
	global_load_dwordx4 v[56:59], v[8:9], off
	global_load_dwordx4 v[60:63], v[10:11], off
	v_lshl_add_u64 v[0:1], s[64:65], 0, v[0:1]
	v_cndmask_b32_e64 v168, v226, v6, s[40:41]
	v_cndmask_b32_e64 v10, 0, v163, s[40:41]
	s_addc_u32 s1, s15, s1
	global_load_dwordx4 v[64:67], v[0:1], off
	v_cndmask_b32_e64 v12, 0, v225, s[40:41]
	v_lshl_add_u64 v[68:69], v[168:169], 1, s[0:1]
	v_max_i32_e32 v0, 0, v10
	v_max_i32_e32 v6, -1, v10
	v_or_b32_e32 v8, 2, v10
	v_add_u32_e32 v10, 3, v10
	v_mad_u64_u32 v[0:1], s[0:1], v0, s33, v[68:69]
	v_add_u32_e32 v6, 1, v6
	v_max_i32_e32 v8, 0, v8
	v_mad_i64_i32 v[10:11], s[0:1], v10, s33, v[68:69]
	v_lshlrev_b32_e32 v168, 1, v12
	s_cmp_ge_u32 s98, 4
	s_cselect_b32 s100, 0, -1
	v_mov_b32_e32 v247, 0
	v_and_b32_e32 v246, s100, v168
	v_mad_u64_u32 v[6:7], s[0:1], v6, s33, v[68:69]
	v_mad_u64_u32 v[8:9], s[0:1], v8, s33, v[68:69]
	global_load_dwordx2 v[150:151], v[0:1], off
	global_load_dwordx2 v[152:153], v[6:7], off
	global_load_dwordx2 v[154:155], v[8:9], off
	global_load_dwordx2 v[148:149], v[10:11], off
	v_lshl_add_u64 v[0:1], v[10:11], 0, v[168:169]
	v_lshl_add_u64 v[6:7], v[0:1], 0, v[168:169]
	v_lshl_add_u64 v[8:9], v[6:7], 0, v[168:169]
	global_load_dwordx2 v[146:147], v[0:1], off
	global_load_dwordx2 v[144:145], v[6:7], off
	global_load_dwordx2 v[142:143], v[8:9], off
	v_lshl_add_u64 v[0:1], v[8:9], 0, v[168:169]
	global_load_dwordx2 v[140:141], v[0:1], off
	v_lshl_add_u64 v[0:1], v[0:1], 0, v[168:169]
	global_load_dwordx2 v[138:139], v[0:1], off
	v_lshl_add_u64 v[0:1], v[0:1], 0, v[168:169]
	global_load_dwordx2 v[136:137], v[0:1], off
	v_lshl_add_u64 v[0:1], v[0:1], 0, v[168:169]
	global_load_dwordx2 v[134:135], v[0:1], off
	v_lshl_add_u64 v[0:1], v[0:1], 0, v[168:169]
	global_load_dwordx2 v[132:133], v[0:1], off
	v_lshl_add_u64 v[0:1], v[0:1], 0, v[168:169]
	global_load_dwordx2 v[130:131], v[0:1], off
	v_lshl_add_u64 v[0:1], v[0:1], 0, v[168:169]
	global_load_dwordx2 v[128:129], v[0:1], off
	v_lshl_add_u64 v[0:1], v[0:1], 0, v[168:169]
	global_load_dwordx2 v[126:127], v[0:1], off
	v_lshl_add_u64 v[0:1], v[0:1], 0, v[168:169]
	global_load_dwordx2 v[124:125], v[0:1], off
	v_lshl_add_u64 v[0:1], v[0:1], 0, v[168:169]
	global_load_dwordx2 v[122:123], v[0:1], off
	v_lshl_add_u64 v[0:1], v[0:1], 0, v[168:169]
	global_load_dwordx2 v[120:121], v[0:1], off
	v_lshl_add_u64 v[0:1], v[0:1], 0, v[168:169]
	global_load_dwordx2 v[118:119], v[0:1], off
	v_lshl_add_u64 v[0:1], v[0:1], 0, v[168:169]
	global_load_dwordx2 v[116:117], v[0:1], off
	v_lshl_add_u64 v[0:1], v[0:1], 0, v[168:169]
	global_load_dwordx2 v[114:115], v[0:1], off
	v_lshl_add_u64 v[0:1], v[0:1], 0, v[168:169]
	global_load_dwordx2 v[112:113], v[0:1], off
	v_lshl_add_u64 v[0:1], v[0:1], 0, v[168:169]
	global_load_dwordx2 v[110:111], v[0:1], off
	v_lshl_add_u64 v[0:1], v[0:1], 0, v[168:169]
	global_load_dwordx2 v[108:109], v[0:1], off
	v_lshl_add_u64 v[0:1], v[0:1], 0, v[168:169]
	global_load_dwordx2 v[106:107], v[0:1], off
	v_lshl_add_u64 v[0:1], v[0:1], 0, v[168:169]
	global_load_dwordx2 v[102:103], v[0:1], off
	v_lshl_add_u64 v[0:1], v[0:1], 0, v[168:169]
	global_load_dwordx2 v[100:101], v[0:1], off
	v_lshl_add_u64 v[0:1], v[0:1], 0, v[168:169]
	global_load_dwordx2 v[94:95], v[0:1], off
	v_lshl_add_u64 v[0:1], v[0:1], 0, v[168:169]
	global_load_dwordx2 v[92:93], v[0:1], off
	v_lshl_add_u64 v[0:1], v[0:1], 0, v[168:169]
	global_load_dwordx2 v[88:89], v[0:1], off
	v_lshl_add_u64 v[0:1], v[0:1], 0, v[168:169]
	global_load_dwordx2 v[86:87], v[0:1], off
	v_lshl_add_u64 v[0:1], v[0:1], 0, v[168:169]
	global_load_dwordx2 v[84:85], v[0:1], off
	v_lshl_add_u64 v[0:1], v[0:1], 0, v[168:169]
	global_load_dwordx2 v[82:83], v[0:1], off
	v_lshl_add_u64 v[0:1], v[0:1], 0, v[168:169]
	global_load_dwordx2 v[80:81], v[0:1], off
	v_lshl_add_u64 v[0:1], v[0:1], 0, v[168:169]
	global_load_dwordx2 v[78:79], v[0:1], off
	s_waitcnt vmcnt(42)
	v_mul_f32_e32 v1, 0x3fb8aa3b, v5
	v_exp_f32_e32 v165, v1
	v_ashrrev_i32_e32 v0, 6, v160
	v_and_b32_e32 v164, 63, v160
	v_and_b32_e32 v240, 32, v164
	v_lshrrev_b32_e32 v241, 2, v240
	v_sub_u32_e32 v240, v240, v241
	v_mov_b32_e32 v241, 0
	v_or_b32_e32 v70, s54, v164
	v_mov_b32_e32 v71, s55
	v_cmp_ne_u32_e64 s[42:43], 3, v0
	v_cmp_eq_u32_e32 vcc, 3, v0
	v_readlane_b32 s57, v245, 30
	v_readlane_b32 s58, v245, 31
	v_readlane_b32 s59, v245, 32
	v_readlane_b32 s60, v245, 33
	v_readlane_b32 s61, v245, 34
	v_readlane_b32 s66, v245, 39
	v_readlane_b32 s67, v245, 40
	v_readlane_b32 s68, v245, 41
	v_readlane_b32 s69, v245, 42
	v_readlane_b32 s70, v245, 43
	v_readlane_b32 s71, v245, 44
	s_and_saveexec_b64 s[6:7], vcc
	s_cbranch_execz .LBB0_222
	v_readlane_b32 s0, v243, 40
	v_lshlrev_b64 v[6:7], 7, v[70:71]
	v_readlane_b32 s1, v243, 41
	s_nop 1
	v_lshl_add_u64 v[6:7], s[0:1], 0, v[6:7]
	v_lshl_add_u64 v[6:7], v[6:7], 0, s[2:3]
	v_add_co_u32_e32 v8, vcc, 0x2000, v6
	global_load_dword v1, v[6:7], off
	s_nop 0
	v_addc_co_u32_e32 v9, vcc, 0, v7, vcc
	global_load_dword v5, v[8:9], off
	s_mov_b32 s0, 0x41a00000
	s_waitcnt vmcnt(1)
	v_add_f32_e32 v1, v162, v1
	v_cmp_nlt_f32_e32 vcc, s0, v1
	s_and_saveexec_b64 s[8:9], vcc
	s_cbranch_execz .LBB0_217
	v_mul_f32_e32 v1, 0x3fb8aa3b, v1
	v_exp_f32_e32 v1, v1
	s_mov_b32 s0, 0x38d1b717
	v_cmp_ngt_f32_e32 vcc, s0, v1
	s_and_saveexec_b64 s[10:11], vcc
	s_cbranch_execz .LBB0_216
	v_add_f32_e32 v1, 1.0, v1
	s_mov_b32 s0, 0x800000
	v_cmp_gt_f32_e32 vcc, s0, v1
	s_mov_b32 s0, 0x3f317217
	s_nop 0
	v_cndmask_b32_e64 v6, 0, 32, vcc
	v_ldexp_f32 v1, v1, v6
	v_log_f32_e32 v1, v1
	s_nop 0
	v_mul_f32_e32 v6, 0x3f317217, v1
	v_fma_f32 v6, v1, s0, -v6
	v_fmac_f32_e32 v6, 0x3377d1cf, v1
	s_mov_b32 s0, 0x7f800000
	v_fmac_f32_e32 v6, 0x3f317217, v1
	v_cmp_lt_f32_e64 s[0:1], |v1|, s0
	s_nop 1
	v_cndmask_b32_e64 v1, v1, v6, s[0:1]
	v_cndmask_b32_e32 v6, 0, v227, vcc
	v_sub_f32_e32 v1, v1, v6

; #define LAS __attribute__((address_space(3)))
; __device__ __forceinline__ unsigned short f2bf(float f) { return (unsigned short)(cvt_pk_bf16(f, 0.f) & 0xffffu); }
; __device__ __forceinline__ void ssd_item(const Params& p, LAS unsigned char* lds, int bl, int head, int dry) {
;     ...
;     f32x16 accS;
; #pragma unroll
;     for (int i = 0; i < 16; ++i) accS[i] = 0.f;
;     for (int c = 0; c < 32; ++c) {
;         const size_t r0 = rowbase + (size_t)c * 128;
;         LAS float* fcs = fs + (c & 1) * 384; LAS float* fdt = fcs + 128; LAS float* fwl = fcs + 256;
;         __syncthreads();
;     ...
;         f32x16 cb[2]; int ti[2], tj[2];
; #pragma unroll
;         for (int q = 0; q < 2; ++q) { const int id = w + 8 * q; ti[q] = id >> 2; tj[q] = id & 3;
; #pragma unroll
;             for (int i = 0; i < 16; ++i) cb[q][i] = 0.f;
;             if (tj[q] <= ti[q]) cb[q] = mma32_k8(CM + ti[q] * 32 * SLD, BMm + tj[q] * 32 * SLD, cb[q], lane); }
;         __syncthreads();
; #pragma unroll
;         for (int q = 0; q < 2; ++q) if (tj[q] <= ti[q]) {
;             const int s = tj[q] * 32 + cl; const float css = fcs[s];
; #pragma unroll
;             for (int r = 0; r < 16; ++r) { const int l = ti[q] * 32 + (r & 3) + 8 * (r >> 2) + rsub;
;                 const float mv = (s <= l) ? cb[q][r] * __expf(fcs[l] - css) : 0.f; BMm[l * SLD + s] = f2bf(mv); } }
.LBB0_222:
	s_or_b64 exec, exec, s[6:7]
	v_and_b32_e32 v10, 3, v0
	v_lshrrev_b32_e32 v6, 3, v160
	v_and_b32_e32 v12, 31, v160
	s_xor_b64 s[34:35], s[4:5], -1
	v_ashrrev_i32_e32 v1, 7, v160
	v_and_b32_e32 v11, 4, v6
	v_and_b32_e32 v166, 3, v3
	v_lshlrev_b32_e32 v3, 6, v10
	v_lshlrev_b32_e32 v6, 1, v12
	v_readlane_b32 s4, v243, 3
	v_readlane_b32 s0, v243, 40
	v_readlane_b32 s1, v243, 41
	v_add3_u32 v3, s4, v3, v6
	s_add_u32 s52, s0, s2
	v_lshlrev_b32_e32 v6, 5, v1
	s_addc_u32 s53, s1, 0
	v_ashrrev_i32_e32 v73, 31, v6
	v_or_b32_e32 v72, v6, v12
	s_lshl_b32 s0, s12, 7
	v_lshlrev_b32_e32 v6, 5, v0
	s_add_u32 s0, s14, s0
	v_and_b32_e32 v13, 32, v6
	s_addc_u32 s1, s15, 0
	v_lshlrev_b32_e32 v6, 1, v13
	v_mov_b32_e32 v7, v169
	v_lshl_add_u64 v[6:7], s[0:1], 0, v[6:7]
	v_lshlrev_b32_e32 v8, 1, v11
	v_mov_b32_e32 v9, v169
	v_readlane_b32 s0, v243, 5
	v_lshl_add_u64 v[74:75], v[6:7], 0, v[8:9]
	v_ashrrev_i32_e32 v5, 8, v160
	v_mov_b32_e32 v6, s0
	v_readlane_b32 s0, v243, 4
	v_mul_u32_u24_e32 v9, 0x88, v12
	v_lshrrev_b32_e32 v14, 1, v160
	v_mov_b32_e32 v7, s0
	s_movk_i32 s2, 0x2200
	v_mul_u32_u24_e32 v16, 0x88, v13
	v_lshl_or_b32 v167, v5, 5, v11
	v_cndmask_b32_e64 v8, v6, v7, s[24:25]
	s_movk_i32 s1, 0x110
	v_lshlrev_b32_e32 v9, 1, v9
	v_and_b32_e32 v14, 16, v14
	v_lshlrev_b32_e32 v172, 1, v1
	v_mul_lo_u32 v17, v1, s2
	v_cmp_lt_i32_e64 s[44:45], -1, v1
	v_lshlrev_b32_e32 v1, 1, v16
	v_mad_i32_i24 v7, v5, s2, v7
	v_lshl_or_b32 v179, v10, 5, v12
	v_lshl_add_u32 v4, v2, 1, v4
	v_mul_lo_u32 v2, v2, s1
	v_add_u32_e32 v16, s4, v1
	v_add3_u32 v175, v7, v9, v14
	v_lshlrev_b32_e32 v7, 6, v166
	v_cmp_le_u32_e64 s[4:5], v179, v167
	v_add3_u32 v178, v8, v2, v7
	v_lshl_add_u32 v178, s99, 1, v178
	v_or_b32_e32 v7, 1, v167
	v_writelane_b32 v243, s4, 43
	v_or_b32_e32 v8, 2, v167
	v_add_u32_e32 v0, 8, v0
	v_writelane_b32 v243, s5, 44
	v_cmp_le_u32_e64 s[4:5], v179, v7
	v_ashrrev_i32_e32 v0, 2, v0
	v_lshl_or_b32 v181, v0, 5, v11
	v_writelane_b32 v243, s4, 45
	v_lshlrev_b32_e32 v170, 5, v166
	v_add_u32_e32 v170, s99, v170
	v_mad_u32_u24 v6, v10, s2, v6
	v_writelane_b32 v243, s5, 46
	v_cmp_le_u32_e64 s[4:5], v179, v8
	v_or_b32_e32 v8, 3, v167
	v_add3_u32 v15, 0, v9, v14
	v_writelane_b32 v243, s4, 47
	v_add3_u32 v174, v16, v9, v14
	v_or_b32_e32 v13, v13, v11
	v_writelane_b32 v243, s5, 48
	v_cmp_le_u32_e64 s[4:5], v179, v8
	v_or_b32_e32 v8, 8, v167
	v_lshl_add_u32 v16, v72, 1, s0
	v_writelane_b32 v243, s4, 49
	v_add3_u32 v176, v6, v9, v14
	v_or_b32_e32 v2, 8, v170
	v_writelane_b32 v243, s5, 50
	v_cmp_le_u32_e64 s[4:5], v179, v8
	v_or_b32_e32 v8, 9, v167
	v_add_u32_e32 v9, v14, v9
	v_writelane_b32 v243, s4, 51
	v_mul_i32_i24_e32 v18, 0x2200, v5
	v_mul_lo_u32 v177, v167, s1
	v_writelane_b32 v243, s5, 52
	v_cmp_le_u32_e64 s[4:5], v179, v8
	v_or_b32_e32 v8, 10, v167
	v_mul_u32_u24_e32 v6, 0x2200, v166
	v_writelane_b32 v243, s4, 53
	v_mul_u32_u24_e32 v2, 0x110, v2
	v_cmp_le_i32_e64 s[46:47], v10, v5
	v_writelane_b32 v243, s5, 54
	v_cmp_le_u32_e64 s[4:5], v179, v8
	v_or_b32_e32 v8, 11, v167
	v_cmp_le_u32_e64 s[64:65], v179, v8
	v_or_b32_e32 v8, 16, v167
	v_cmp_le_u32_e64 s[66:67], v179, v8
	v_or_b32_e32 v8, 17, v167
	v_cmp_le_u32_e64 s[68:69], v179, v8
	v_or_b32_e32 v8, 18, v167
	v_cmp_le_u32_e64 s[70:71], v179, v8
	v_or_b32_e32 v8, 19, v167
	v_cmp_le_u32_e64 s[72:73], v179, v8
	v_or_b32_e32 v8, 24, v167
	v_cmp_le_u32_e64 s[74:75], v179, v8
	v_or_b32_e32 v8, 25, v167
	v_cmp_le_u32_e64 s[76:77], v179, v8
	v_or_b32_e32 v8, 26, v167
	v_cmp_le_u32_e64 s[78:79], v179, v8
	v_or_b32_e32 v8, 27, v167
	v_cmp_le_u32_e64 s[80:81], v179, v8
	v_or_b32_e32 v8, 1, v181
	v_cmp_le_u32_e64 s[84:85], v179, v8
	v_or_b32_e32 v8, 2, v181
	v_cmp_le_u32_e64 s[86:87], v179, v8
	v_or_b32_e32 v8, 3, v181
	v_cmp_le_u32_e64 s[88:89], v179, v8
	v_or_b32_e32 v8, 8, v181
	v_cmp_le_u32_e64 s[90:91], v179, v8
	v_or_b32_e32 v8, 9, v181
	v_cmp_le_u32_e64 s[92:93], v179, v8
	v_or_b32_e32 v8, 10, v181
	v_cmp_le_u32_e64 s[94:95], v179, v8
	v_or_b32_e32 v8, 11, v181
	v_cmp_le_u32_e64 s[96:97], v179, v8
	v_or_b32_e32 v8, 16, v181
	v_writelane_b32 v243, s4, 55
	v_cmp_le_u32_e64 s[30:31], v179, v8
	v_or_b32_e32 v8, 17, v181
	v_writelane_b32 v243, s5, 56
	v_cmp_le_u32_e64 s[4:5], v179, v8
	v_or_b32_e32 v8, 18, v181
	v_cmp_le_u32_e64 s[6:7], v179, v8
	v_or_b32_e32 v8, 19, v181
	v_cmp_le_u32_e64 s[8:9], v179, v8
	v_or_b32_e32 v8, 24, v181
	v_cmp_le_u32_e64 s[10:11], v179, v8
	v_or_b32_e32 v8, 25, v181
	v_cmp_le_u32_e64 s[12:13], v179, v8
	v_or_b32_e32 v8, 26, v181
	v_cmp_le_u32_e64 s[14:15], v179, v8
	v_or_b32_e32 v8, 27, v181
	v_readlane_b32 s0, v243, 1
	v_cmp_le_i32_e64 s[48:49], v10, v0
	v_mul_lo_u32 v5, v0, s2
	v_lshl_add_u32 v180, v179, 1, 0
	v_mul_lo_u32 v7, v7, s1
	v_mul_lo_u32 v0, v181, s1
	v_cmp_le_u32_e64 s[16:17], v179, v8
	v_mul_u32_u24_e32 v8, 0x110, v13
	v_add3_u32 v183, v9, v17, s0
	v_readlane_b32 s0, v243, 6
	v_mov_b32_e32 v185, 0
	v_mad_u32_u24 v171, v10, s2, v15
	v_add_u32_e32 v173, v15, v17
	v_ashrrev_i32_e32 v77, 31, v72
	v_mov_b32_e32 v76, v72
	v_cmp_le_u32_e64 s[82:83], v179, v181
	s_mov_b32 s58, 0
	v_cmp_eq_u32_e64 s[18:19], 0, v164
	v_cmp_gt_u32_e64 s[20:21], 2, v164
	v_cmp_gt_u32_e64 s[22:23], 4, v164
	v_cndmask_b32_e64 v182, v229, v230, s[24:25]
	v_cmp_gt_u32_e64 s[24:25], 8, v164
	v_add3_u32 v184, v9, v1, s0
	v_add_u32_e32 v186, v3, v177
	v_add_u32_e32 v187, v4, v6
	v_add_u32_e32 v187, s101, v187
	v_add_u32_e32 v188, v15, v18
	v_add_u32_e32 v189, v15, v5
	v_add_u32_e32 v190, v16, v8
	v_add_u32_e32 v191, v4, v2
	v_add_u32_e32 v192, v180, v7
	v_add_u32_e32 v193, v180, v0
	v_mov_b32_e32 v0, 0
	v_mov_b32_e32 v1, v185
	v_mov_b32_e32 v2, v185
	v_mov_b32_e32 v3, v185
	v_mov_b32_e32 v4, v185
	v_mov_b32_e32 v5, v185
	v_mov_b32_e32 v6, v185
	v_mov_b32_e32 v7, v185
	v_mov_b32_e32 v8, v185
	v_mov_b32_e32 v9, v185
	v_mov_b32_e32 v10, v185
	v_mov_b32_e32 v11, v185
	v_mov_b32_e32 v12, v185
	v_mov_b32_e32 v13, v185
	v_mov_b32_e32 v14, v185
	v_mov_b32_e32 v15, v185
	v_cmp_gt_u32_e64 s[26:27], 16, v164
	v_cmp_gt_u32_e64 s[28:29], 32, v164
	s_waitcnt vmcnt(0)
	s_branch .LBB0_224
